# GEMM main loops: the two k-chunk MFMAs of each accumulator issued back to back (SrcC forwarding), accumulators visited in serpentine operand order, chunk order alternating so consecutive MFMAs share a
# speedup vs baseline: 1.0132x; 1.0070x over previous
.LBB0_202:
	ds_read_b128 v[112:115], v218
	ds_read_b128 v[116:119], v218 offset:1024
	ds_read_b128 v[120:123], v218 offset:2048
	ds_read_b128 v[124:127], v218 offset:3072
	s_waitcnt vmcnt(0)
	ds_read_b128 v[128:131], v219
	ds_read_b128 v[132:135], v219 offset:1024
	ds_read_b128 v[136:139], v219 offset:2048
	ds_read_b128 v[140:143], v219 offset:3072
	s_add_u32 s69, s12, 0xfffc0080
	s_addc_u32 s73, s13, -1
	s_cmp_eq_u32 s68, 12
	s_cselect_b32 s83, s1, s73
	s_cselect_b32 s82, s2, s69
	s_cselect_b32 s81, s3, s66
	s_cselect_b32 s80, s34, s35
	v_lshl_add_u64 v[230:231], s[12:13], 0, v[192:193]
	s_add_i32 m0, s15, 0xc000
	ds_read_b128 v[152:155], v220
	ds_read_b128 v[156:159], v220 offset:1024
	ds_read_b128 v[160:163], v220 offset:2048
	ds_read_b128 v[164:167], v220 offset:3072
	ds_read_b128 v[200:203], v220 offset:4096
	ds_read_b128 v[204:207], v220 offset:5120
	ds_read_b128 v[208:211], v220 offset:6144
	ds_read_b128 v[226:229], v220 offset:7168
	global_load_lds_dwordx4 v[230:231], off
	v_lshl_add_u64 v[230:231], s[12:13], 0, v[194:195]
	s_add_i32 m0, s15, 0xe000
	s_nop 0
	global_load_lds_dwordx4 v[230:231], off
	s_waitcnt vmcnt(8)
	s_waitcnt lgkmcnt(0)
	s_barrier
	s_setprio 1
	s_waitcnt lgkmcnt(0)
	v_mfma_f32_16x16x32_bf16 v[172:175], v[112:115], v[152:155], v[172:175]
	v_mfma_f32_16x16x32_bf16 v[172:175], v[116:119], v[156:159], v[172:175]
	v_mfma_f32_16x16x32_bf16 v[168:171], v[124:127], v[156:159], v[168:171]
	v_mfma_f32_16x16x32_bf16 v[168:171], v[120:123], v[152:155], v[168:171]
	v_mfma_f32_16x16x32_bf16 v[104:107], v[120:123], v[160:163], v[104:107]
	v_mfma_f32_16x16x32_bf16 v[104:107], v[124:127], v[164:167], v[104:107]
	v_mfma_f32_16x16x32_bf16 v[108:111], v[116:119], v[164:167], v[108:111]
	v_mfma_f32_16x16x32_bf16 v[108:111], v[112:115], v[160:163], v[108:111]
	v_mfma_f32_16x16x32_bf16 v[92:95], v[112:115], v[200:203], v[92:95]
	v_mfma_f32_16x16x32_bf16 v[92:95], v[116:119], v[204:207], v[92:95]
	v_mfma_f32_16x16x32_bf16 v[88:91], v[124:127], v[204:207], v[88:91]
	v_mfma_f32_16x16x32_bf16 v[88:91], v[120:123], v[200:203], v[88:91]
	v_mfma_f32_16x16x32_bf16 v[72:75], v[120:123], v[208:211], v[72:75]
	v_mfma_f32_16x16x32_bf16 v[72:75], v[124:127], v[226:229], v[72:75]
	v_mfma_f32_16x16x32_bf16 v[76:79], v[116:119], v[226:229], v[76:79]
	v_mfma_f32_16x16x32_bf16 v[76:79], v[112:115], v[208:211], v[76:79]
	s_setprio 0
	s_setprio 1
	v_mfma_f32_16x16x32_bf16 v[148:151], v[128:131], v[152:155], v[148:151]
	v_mfma_f32_16x16x32_bf16 v[148:151], v[132:135], v[156:159], v[148:151]
	v_mfma_f32_16x16x32_bf16 v[144:147], v[140:143], v[156:159], v[144:147]
	v_mfma_f32_16x16x32_bf16 v[144:147], v[136:139], v[152:155], v[144:147]
	v_mfma_f32_16x16x32_bf16 v[96:99], v[136:139], v[160:163], v[96:99]
	v_mfma_f32_16x16x32_bf16 v[96:99], v[140:143], v[164:167], v[96:99]
	v_mfma_f32_16x16x32_bf16 v[100:103], v[132:135], v[164:167], v[100:103]
	v_mfma_f32_16x16x32_bf16 v[100:103], v[128:131], v[160:163], v[100:103]
	v_mfma_f32_16x16x32_bf16 v[84:87], v[128:131], v[200:203], v[84:87]
	v_mfma_f32_16x16x32_bf16 v[84:87], v[132:135], v[204:207], v[84:87]
	v_mfma_f32_16x16x32_bf16 v[80:83], v[140:143], v[204:207], v[80:83]
	v_mfma_f32_16x16x32_bf16 v[80:83], v[136:139], v[200:203], v[80:83]
	v_mfma_f32_16x16x32_bf16 v[64:67], v[136:139], v[208:211], v[64:67]
	v_mfma_f32_16x16x32_bf16 v[64:67], v[140:143], v[226:229], v[64:67]
	v_mfma_f32_16x16x32_bf16 v[68:71], v[132:135], v[226:229], v[68:71]
	v_mfma_f32_16x16x32_bf16 v[68:71], v[128:131], v[208:211], v[68:71]
	s_setprio 0
	s_barrier
	s_add_i32 s69, s59, s14
	v_lshl_add_u64 v[230:231], s[80:81], 0, v[178:179]
	s_mov_b32 m0, s69
	ds_read_b128 v[152:155], v220 offset:16384
	ds_read_b128 v[156:159], v220 offset:17408
	ds_read_b128 v[160:163], v220 offset:18432
	ds_read_b128 v[164:167], v220 offset:19456
	ds_read_b128 v[200:203], v220 offset:20480
	ds_read_b128 v[204:207], v220 offset:21504
	ds_read_b128 v[208:211], v220 offset:22528
	ds_read_b128 v[226:229], v220 offset:23552
	global_load_lds_dwordx4 v[230:231], off
	s_add_i32 m0, s69, 0x2000
	s_add_u32 s86, s80, 0x40000
	v_lshl_add_u64 v[232:233], s[80:81], 0, v[182:183]
	s_addc_u32 s87, s81, 0
	s_add_i32 s69, s65, s14
	global_load_lds_dwordx4 v[232:233], off
	v_lshl_add_u64 v[234:235], s[86:87], 0, v[178:179]
	s_mov_b32 m0, s69
	v_lshl_add_u64 v[236:237], s[82:83], 0, v[180:181]
	global_load_lds_dwordx4 v[234:235], off
	v_lshl_add_u64 v[234:235], s[86:87], 0, v[182:183]
	s_add_i32 m0, s69, 0x2000
	s_nop 0
	global_load_lds_dwordx4 v[234:235], off
	v_lshl_add_u64 v[234:235], s[82:83], 0, v[176:177]
	s_mov_b32 m0, s15
	s_nop 0
	global_load_lds_dwordx4 v[234:235], off
	s_mov_b32 m0, s52
	s_nop 0
	global_load_lds_dwordx4 v[236:237], off
	s_waitcnt vmcnt(8)
	s_waitcnt lgkmcnt(0)
	s_barrier
	s_setprio 1
	s_waitcnt lgkmcnt(0)
	v_mfma_f32_16x16x32_bf16 v[60:63], v[112:115], v[152:155], v[60:63]
	v_mfma_f32_16x16x32_bf16 v[60:63], v[116:119], v[156:159], v[60:63]
	v_mfma_f32_16x16x32_bf16 v[56:59], v[124:127], v[156:159], v[56:59]
	v_mfma_f32_16x16x32_bf16 v[56:59], v[120:123], v[152:155], v[56:59]
	v_mfma_f32_16x16x32_bf16 v[40:43], v[120:123], v[160:163], v[40:43]
	v_mfma_f32_16x16x32_bf16 v[40:43], v[124:127], v[164:167], v[40:43]
	v_mfma_f32_16x16x32_bf16 v[44:47], v[116:119], v[164:167], v[44:47]
	v_mfma_f32_16x16x32_bf16 v[44:47], v[112:115], v[160:163], v[44:47]
	v_mfma_f32_16x16x32_bf16 v[28:31], v[112:115], v[200:203], v[28:31]
	v_mfma_f32_16x16x32_bf16 v[28:31], v[116:119], v[204:207], v[28:31]
	v_mfma_f32_16x16x32_bf16 v[24:27], v[124:127], v[204:207], v[24:27]
	v_mfma_f32_16x16x32_bf16 v[24:27], v[120:123], v[200:203], v[24:27]
	v_mfma_f32_16x16x32_bf16 v[8:11], v[120:123], v[208:211], v[8:11]
	v_mfma_f32_16x16x32_bf16 v[8:11], v[124:127], v[226:229], v[8:11]
	v_mfma_f32_16x16x32_bf16 v[12:15], v[116:119], v[226:229], v[12:15]
	v_mfma_f32_16x16x32_bf16 v[12:15], v[112:115], v[208:211], v[12:15]
	s_setprio 0
	s_setprio 1
	v_mfma_f32_16x16x32_bf16 v[52:55], v[128:131], v[152:155], v[52:55]
	v_mfma_f32_16x16x32_bf16 v[52:55], v[132:135], v[156:159], v[52:55]
	v_mfma_f32_16x16x32_bf16 v[48:51], v[140:143], v[156:159], v[48:51]
	v_mfma_f32_16x16x32_bf16 v[48:51], v[136:139], v[152:155], v[48:51]
	v_mfma_f32_16x16x32_bf16 v[32:35], v[136:139], v[160:163], v[32:35]
	v_mfma_f32_16x16x32_bf16 v[32:35], v[140:143], v[164:167], v[32:35]
	v_mfma_f32_16x16x32_bf16 v[36:39], v[132:135], v[164:167], v[36:39]
	v_mfma_f32_16x16x32_bf16 v[36:39], v[128:131], v[160:163], v[36:39]
	v_mfma_f32_16x16x32_bf16 v[20:23], v[128:131], v[200:203], v[20:23]
	v_mfma_f32_16x16x32_bf16 v[20:23], v[132:135], v[204:207], v[20:23]
	v_mfma_f32_16x16x32_bf16 v[16:19], v[140:143], v[204:207], v[16:19]
	v_mfma_f32_16x16x32_bf16 v[16:19], v[136:139], v[200:203], v[16:19]
	v_mfma_f32_16x16x32_bf16 v[0:3], v[136:139], v[208:211], v[0:3]
	v_mfma_f32_16x16x32_bf16 v[0:3], v[140:143], v[226:229], v[0:3]
	v_mfma_f32_16x16x32_bf16 v[4:7], v[132:135], v[226:229], v[4:7]
	v_mfma_f32_16x16x32_bf16 v[4:7], v[128:131], v[208:211], v[4:7]
	s_setprio 0
	s_barrier
	s_add_i32 s69, 0, 0x18000
	s_add_i32 s73, 0, 0x1c000
	v_add_u32_e32 v124, s69, v212
	v_add_u32_e32 v140, s73, v212
	ds_read_b128 v[112:115], v124
	ds_read_b128 v[116:119], v124 offset:1024
	ds_read_b128 v[120:123], v124 offset:2048
	ds_read_b128 v[124:127], v124 offset:3072
	ds_read_b128 v[128:131], v140
	ds_read_b128 v[132:135], v140 offset:1024
	ds_read_b128 v[136:139], v140 offset:2048
	ds_read_b128 v[140:143], v140 offset:3072
	s_add_u32 s82, s82, 0x40000
	s_addc_u32 s83, s83, 0
	s_mov_b32 m0, s53
	v_lshl_add_u64 v[238:239], s[82:83], 0, v[176:177]
	ds_read_b128 v[152:155], v220 offset:32768
	ds_read_b128 v[156:159], v220 offset:33792
	ds_read_b128 v[160:163], v220 offset:34816
	ds_read_b128 v[164:167], v220 offset:35840
	ds_read_b128 v[200:203], v220 offset:36864
	ds_read_b128 v[204:207], v220 offset:37888
	ds_read_b128 v[208:211], v220 offset:38912
	ds_read_b128 v[226:229], v220 offset:39936
	global_load_lds_dwordx4 v[238:239], off
	v_lshl_add_u64 v[238:239], s[82:83], 0, v[180:181]
	s_mov_b32 m0, s54
	s_nop 0
	global_load_lds_dwordx4 v[238:239], off
	s_waitcnt vmcnt(8)
	s_waitcnt lgkmcnt(0)
	s_barrier
	s_setprio 1
	s_waitcnt lgkmcnt(0)
	v_mfma_f32_16x16x32_bf16 v[172:175], v[112:115], v[152:155], v[172:175]
	v_mfma_f32_16x16x32_bf16 v[172:175], v[116:119], v[156:159], v[172:175]
	v_mfma_f32_16x16x32_bf16 v[168:171], v[124:127], v[156:159], v[168:171]
	v_mfma_f32_16x16x32_bf16 v[168:171], v[120:123], v[152:155], v[168:171]
	v_mfma_f32_16x16x32_bf16 v[104:107], v[120:123], v[160:163], v[104:107]
	v_mfma_f32_16x16x32_bf16 v[104:107], v[124:127], v[164:167], v[104:107]
	v_mfma_f32_16x16x32_bf16 v[108:111], v[116:119], v[164:167], v[108:111]
	v_mfma_f32_16x16x32_bf16 v[108:111], v[112:115], v[160:163], v[108:111]
	v_mfma_f32_16x16x32_bf16 v[92:95], v[112:115], v[200:203], v[92:95]
	v_mfma_f32_16x16x32_bf16 v[92:95], v[116:119], v[204:207], v[92:95]
	v_mfma_f32_16x16x32_bf16 v[88:91], v[124:127], v[204:207], v[88:91]
	v_mfma_f32_16x16x32_bf16 v[88:91], v[120:123], v[200:203], v[88:91]
	v_mfma_f32_16x16x32_bf16 v[72:75], v[120:123], v[208:211], v[72:75]
	v_mfma_f32_16x16x32_bf16 v[72:75], v[124:127], v[226:229], v[72:75]
	v_mfma_f32_16x16x32_bf16 v[76:79], v[116:119], v[226:229], v[76:79]
	v_mfma_f32_16x16x32_bf16 v[76:79], v[112:115], v[208:211], v[76:79]
	s_setprio 0
	s_setprio 1
	v_mfma_f32_16x16x32_bf16 v[148:151], v[128:131], v[152:155], v[148:151]
	v_mfma_f32_16x16x32_bf16 v[148:151], v[132:135], v[156:159], v[148:151]
	v_mfma_f32_16x16x32_bf16 v[144:147], v[140:143], v[156:159], v[144:147]
	v_mfma_f32_16x16x32_bf16 v[144:147], v[136:139], v[152:155], v[144:147]
	v_mfma_f32_16x16x32_bf16 v[96:99], v[136:139], v[160:163], v[96:99]
	v_mfma_f32_16x16x32_bf16 v[96:99], v[140:143], v[164:167], v[96:99]
	v_mfma_f32_16x16x32_bf16 v[100:103], v[132:135], v[164:167], v[100:103]
	v_mfma_f32_16x16x32_bf16 v[100:103], v[128:131], v[160:163], v[100:103]
	v_mfma_f32_16x16x32_bf16 v[84:87], v[128:131], v[200:203], v[84:87]
	v_mfma_f32_16x16x32_bf16 v[84:87], v[132:135], v[204:207], v[84:87]
	v_mfma_f32_16x16x32_bf16 v[80:83], v[140:143], v[204:207], v[80:83]
	v_mfma_f32_16x16x32_bf16 v[80:83], v[136:139], v[200:203], v[80:83]
	v_mfma_f32_16x16x32_bf16 v[64:67], v[136:139], v[208:211], v[64:67]
	v_mfma_f32_16x16x32_bf16 v[64:67], v[140:143], v[226:229], v[64:67]
	v_mfma_f32_16x16x32_bf16 v[68:71], v[132:135], v[226:229], v[68:71]
	v_mfma_f32_16x16x32_bf16 v[68:71], v[128:131], v[208:211], v[68:71]
	s_setprio 0
	s_barrier
	s_add_i32 s69, s69, s14
	v_lshl_add_u64 v[230:231], v[230:231], 0, s[40:41]
	s_mov_b32 m0, s69
	ds_read_b128 v[152:155], v220 offset:49152
	ds_read_b128 v[156:159], v220 offset:50176
	ds_read_b128 v[160:163], v220 offset:51200
	ds_read_b128 v[164:167], v220 offset:52224
	ds_read_b128 v[200:203], v220 offset:53248
	ds_read_b128 v[204:207], v220 offset:54272
	ds_read_b128 v[208:211], v220 offset:55296
	ds_read_b128 v[226:229], v220 offset:56320
	global_load_lds_dwordx4 v[230:231], off
	s_add_i32 m0, s69, 0x2000
	s_add_u32 s80, s80, 0x40080
	v_lshl_add_u64 v[230:231], v[232:233], 0, s[40:41]
	s_addc_u32 s81, s81, 0
	s_add_i32 s69, s73, s14
	global_load_lds_dwordx4 v[230:231], off
	v_lshl_add_u64 v[230:231], s[80:81], 0, v[178:179]
	s_mov_b32 m0, s69
	s_nop 0
	global_load_lds_dwordx4 v[230:231], off
	v_lshl_add_u64 v[230:231], s[80:81], 0, v[182:183]
	s_add_i32 m0, s69, 0x2000
	s_nop 0
	global_load_lds_dwordx4 v[230:231], off
	v_lshl_add_u64 v[230:231], v[234:235], 0, s[40:41]
	s_mov_b32 m0, s57
	s_nop 0
	global_load_lds_dwordx4 v[230:231], off
	v_lshl_add_u64 v[230:231], v[236:237], 0, s[40:41]
	s_mov_b32 m0, s58
	s_nop 0
	global_load_lds_dwordx4 v[230:231], off
	s_waitcnt vmcnt(8)
	s_waitcnt lgkmcnt(0)
	s_barrier
	s_setprio 1
	s_waitcnt lgkmcnt(0)
	v_mfma_f32_16x16x32_bf16 v[60:63], v[112:115], v[152:155], v[60:63]
	v_mfma_f32_16x16x32_bf16 v[60:63], v[116:119], v[156:159], v[60:63]
	v_mfma_f32_16x16x32_bf16 v[56:59], v[124:127], v[156:159], v[56:59]
	v_mfma_f32_16x16x32_bf16 v[56:59], v[120:123], v[152:155], v[56:59]
	v_mfma_f32_16x16x32_bf16 v[40:43], v[120:123], v[160:163], v[40:43]
	v_mfma_f32_16x16x32_bf16 v[40:43], v[124:127], v[164:167], v[40:43]
	v_mfma_f32_16x16x32_bf16 v[44:47], v[116:119], v[164:167], v[44:47]
	v_mfma_f32_16x16x32_bf16 v[44:47], v[112:115], v[160:163], v[44:47]
	v_mfma_f32_16x16x32_bf16 v[28:31], v[112:115], v[200:203], v[28:31]
	v_mfma_f32_16x16x32_bf16 v[28:31], v[116:119], v[204:207], v[28:31]
	v_mfma_f32_16x16x32_bf16 v[24:27], v[124:127], v[204:207], v[24:27]
	v_mfma_f32_16x16x32_bf16 v[24:27], v[120:123], v[200:203], v[24:27]
	v_mfma_f32_16x16x32_bf16 v[8:11], v[120:123], v[208:211], v[8:11]
	v_mfma_f32_16x16x32_bf16 v[8:11], v[124:127], v[226:229], v[8:11]
	v_mfma_f32_16x16x32_bf16 v[12:15], v[116:119], v[226:229], v[12:15]
	v_mfma_f32_16x16x32_bf16 v[12:15], v[112:115], v[208:211], v[12:15]
	s_setprio 0
	s_setprio 1
	v_mfma_f32_16x16x32_bf16 v[52:55], v[128:131], v[152:155], v[52:55]
	v_mfma_f32_16x16x32_bf16 v[52:55], v[132:135], v[156:159], v[52:55]
	v_mfma_f32_16x16x32_bf16 v[48:51], v[140:143], v[156:159], v[48:51]
	v_mfma_f32_16x16x32_bf16 v[48:51], v[136:139], v[152:155], v[48:51]
	v_mfma_f32_16x16x32_bf16 v[32:35], v[136:139], v[160:163], v[32:35]
	v_mfma_f32_16x16x32_bf16 v[32:35], v[140:143], v[164:167], v[32:35]
	v_mfma_f32_16x16x32_bf16 v[36:39], v[132:135], v[164:167], v[36:39]
	v_mfma_f32_16x16x32_bf16 v[36:39], v[128:131], v[160:163], v[36:39]
	v_mfma_f32_16x16x32_bf16 v[20:23], v[128:131], v[200:203], v[20:23]
	v_mfma_f32_16x16x32_bf16 v[20:23], v[132:135], v[204:207], v[20:23]
	v_mfma_f32_16x16x32_bf16 v[16:19], v[140:143], v[204:207], v[16:19]
	v_mfma_f32_16x16x32_bf16 v[16:19], v[136:139], v[200:203], v[16:19]
	v_mfma_f32_16x16x32_bf16 v[0:3], v[136:139], v[208:211], v[0:3]
	v_mfma_f32_16x16x32_bf16 v[0:3], v[140:143], v[226:229], v[0:3]
	v_mfma_f32_16x16x32_bf16 v[4:7], v[132:135], v[226:229], v[4:7]
	v_mfma_f32_16x16x32_bf16 v[4:7], v[128:131], v[208:211], v[4:7]
	s_setprio 0
	s_barrier
	s_add_i32 s68, s68, 2
	s_add_u32 s12, s12, 0x100
	s_addc_u32 s13, s13, 0
	s_add_u32 s35, s35, 0x100
	s_addc_u32 s66, s66, 0
	s_cmp_gt_u32 s68, 13
	s_cbranch_scc0 .LBB0_202
	s_and_b64 vcc, exec, s[42:43]
	s_cbranch_vccz .LBB0_205
	s_barrier

.LBB0_646:
	ds_read_b128 v[88:91], v236
	ds_read_b128 v[100:103], v236 offset:1024
	ds_read_b128 v[112:115], v236 offset:2048
	ds_read_b128 v[124:127], v236 offset:3072
	ds_read_b128 v[136:139], v237
	ds_read_b128 v[148:151], v237 offset:1024
	ds_read_b128 v[152:155], v237 offset:2048
	ds_read_b128 v[156:159], v237 offset:3072
	s_add_u32 s44, s42, 0xfffc0080
	s_addc_u32 s45, s43, -1
	s_cmp_eq_u32 s57, 12
	s_cselect_b32 s47, s31, s45
	s_cselect_b32 s46, s41, s44
	s_cselect_b32 s45, s29, s56
	s_cselect_b32 s44, s54, s55
	v_lshl_add_u64 v[208:209], s[42:43], 0, v[194:195]
	s_add_i32 m0, s3, 0xc000
	ds_read_b128 v[160:163], v238
	ds_read_b128 v[164:167], v238 offset:1024
	ds_read_b128 v[168:171], v238 offset:2048
	ds_read_b128 v[172:175], v238 offset:3072
	ds_read_b128 v[176:179], v238 offset:4096
	ds_read_b128 v[180:183], v238 offset:5120
	ds_read_b128 v[202:205], v238 offset:6144
	ds_read_b128 v[228:231], v238 offset:7168
	global_load_lds_dwordx4 v[208:209], off
	v_lshl_add_u64 v[208:209], s[42:43], 0, v[196:197]
	s_add_i32 m0, s3, 0xe000
	s_nop 0
	global_load_lds_dwordx4 v[208:209], off
	s_waitcnt vmcnt(8)
	s_waitcnt lgkmcnt(0)
	s_barrier
	s_setprio 1
	s_waitcnt lgkmcnt(0)
	v_mfma_f32_16x16x32_bf16 v[144:147], v[88:91], v[160:163], v[144:147]
	v_mfma_f32_16x16x32_bf16 v[144:147], v[100:103], v[164:167], v[144:147]
	v_mfma_f32_16x16x32_bf16 v[140:143], v[124:127], v[164:167], v[140:143]
	v_mfma_f32_16x16x32_bf16 v[140:143], v[112:115], v[160:163], v[140:143]
	v_mfma_f32_16x16x32_bf16 v[116:119], v[112:115], v[168:171], v[116:119]
	v_mfma_f32_16x16x32_bf16 v[116:119], v[124:127], v[172:175], v[116:119]
	v_mfma_f32_16x16x32_bf16 v[120:123], v[100:103], v[172:175], v[120:123]
	v_mfma_f32_16x16x32_bf16 v[120:123], v[88:91], v[168:171], v[120:123]
	v_mfma_f32_16x16x32_bf16 v[96:99], v[88:91], v[176:179], v[96:99]
	v_mfma_f32_16x16x32_bf16 v[96:99], v[100:103], v[180:183], v[96:99]
	v_mfma_f32_16x16x32_bf16 v[92:95], v[124:127], v[180:183], v[92:95]
	v_mfma_f32_16x16x32_bf16 v[92:95], v[112:115], v[176:179], v[92:95]
	v_mfma_f32_16x16x32_bf16 v[72:75], v[112:115], v[202:205], v[72:75]
	v_mfma_f32_16x16x32_bf16 v[72:75], v[124:127], v[228:231], v[72:75]
	v_mfma_f32_16x16x32_bf16 v[76:79], v[100:103], v[228:231], v[76:79]
	v_mfma_f32_16x16x32_bf16 v[76:79], v[88:91], v[202:205], v[76:79]
	s_setprio 0
	s_setprio 1
	v_mfma_f32_16x16x32_bf16 v[132:135], v[136:139], v[160:163], v[132:135]
	v_mfma_f32_16x16x32_bf16 v[132:135], v[148:151], v[164:167], v[132:135]
	v_mfma_f32_16x16x32_bf16 v[128:131], v[156:159], v[164:167], v[128:131]
	v_mfma_f32_16x16x32_bf16 v[128:131], v[152:155], v[160:163], v[128:131]
	v_mfma_f32_16x16x32_bf16 v[104:107], v[152:155], v[168:171], v[104:107]
	v_mfma_f32_16x16x32_bf16 v[104:107], v[156:159], v[172:175], v[104:107]
	v_mfma_f32_16x16x32_bf16 v[108:111], v[148:151], v[172:175], v[108:111]
	v_mfma_f32_16x16x32_bf16 v[108:111], v[136:139], v[168:171], v[108:111]
	v_mfma_f32_16x16x32_bf16 v[84:87], v[136:139], v[176:179], v[84:87]
	v_mfma_f32_16x16x32_bf16 v[84:87], v[148:151], v[180:183], v[84:87]
	v_mfma_f32_16x16x32_bf16 v[80:83], v[156:159], v[180:183], v[80:83]
	v_mfma_f32_16x16x32_bf16 v[80:83], v[152:155], v[176:179], v[80:83]
	v_mfma_f32_16x16x32_bf16 v[64:67], v[152:155], v[202:205], v[64:67]
	v_mfma_f32_16x16x32_bf16 v[64:67], v[156:159], v[228:231], v[64:67]
	v_mfma_f32_16x16x32_bf16 v[68:71], v[148:151], v[228:231], v[68:71]
	v_mfma_f32_16x16x32_bf16 v[68:71], v[136:139], v[202:205], v[68:71]
	s_setprio 0
	s_barrier
	s_add_i32 s58, s51, s2
	v_lshl_add_u64 v[208:209], s[44:45], 0, v[186:187]
	s_mov_b32 m0, s58
	ds_read_b128 v[160:163], v238 offset:16384
	ds_read_b128 v[164:167], v238 offset:17408
	ds_read_b128 v[168:171], v238 offset:18432
	ds_read_b128 v[172:175], v238 offset:19456
	ds_read_b128 v[176:179], v238 offset:20480
	ds_read_b128 v[180:183], v238 offset:21504
	ds_read_b128 v[202:205], v238 offset:22528
	ds_read_b128 v[228:231], v238 offset:23552
	global_load_lds_dwordx4 v[208:209], off
	s_add_i32 m0, s58, 0x2000
	s_add_u32 s58, s44, 0x40000
	v_lshl_add_u64 v[212:213], s[44:45], 0, v[190:191]
	s_addc_u32 s59, s45, 0
	s_add_i32 s64, s52, s2
	global_load_lds_dwordx4 v[212:213], off
	v_lshl_add_u64 v[216:217], s[58:59], 0, v[186:187]
	s_mov_b32 m0, s64
	v_lshl_add_u64 v[220:221], s[46:47], 0, v[188:189]
	global_load_lds_dwordx4 v[216:217], off
	v_lshl_add_u64 v[216:217], s[58:59], 0, v[190:191]
	s_add_i32 m0, s64, 0x2000
	s_nop 0
	global_load_lds_dwordx4 v[216:217], off
	v_lshl_add_u64 v[216:217], s[46:47], 0, v[184:185]
	s_mov_b32 m0, s3
	s_nop 0
	global_load_lds_dwordx4 v[216:217], off
	s_mov_b32 m0, s33
	s_nop 0
	global_load_lds_dwordx4 v[220:221], off
	s_waitcnt vmcnt(8)
	s_waitcnt lgkmcnt(0)
	s_barrier
	s_setprio 1
	s_waitcnt lgkmcnt(0)
	v_mfma_f32_16x16x32_bf16 v[60:63], v[88:91], v[160:163], v[60:63]
	v_mfma_f32_16x16x32_bf16 v[60:63], v[100:103], v[164:167], v[60:63]
	v_mfma_f32_16x16x32_bf16 v[56:59], v[124:127], v[164:167], v[56:59]
	v_mfma_f32_16x16x32_bf16 v[56:59], v[112:115], v[160:163], v[56:59]
	v_mfma_f32_16x16x32_bf16 v[40:43], v[112:115], v[168:171], v[40:43]
	v_mfma_f32_16x16x32_bf16 v[40:43], v[124:127], v[172:175], v[40:43]
	v_mfma_f32_16x16x32_bf16 v[44:47], v[100:103], v[172:175], v[44:47]
	v_mfma_f32_16x16x32_bf16 v[44:47], v[88:91], v[168:171], v[44:47]
	v_mfma_f32_16x16x32_bf16 v[28:31], v[88:91], v[176:179], v[28:31]
	v_mfma_f32_16x16x32_bf16 v[28:31], v[100:103], v[180:183], v[28:31]
	v_mfma_f32_16x16x32_bf16 v[24:27], v[124:127], v[180:183], v[24:27]
	v_mfma_f32_16x16x32_bf16 v[24:27], v[112:115], v[176:179], v[24:27]
	v_mfma_f32_16x16x32_bf16 v[8:11], v[112:115], v[202:205], v[8:11]
	v_mfma_f32_16x16x32_bf16 v[8:11], v[124:127], v[228:231], v[8:11]
	v_mfma_f32_16x16x32_bf16 v[12:15], v[100:103], v[228:231], v[12:15]
	v_mfma_f32_16x16x32_bf16 v[12:15], v[88:91], v[202:205], v[12:15]
	s_setprio 0
	s_setprio 1
	v_mfma_f32_16x16x32_bf16 v[52:55], v[136:139], v[160:163], v[52:55]
	v_mfma_f32_16x16x32_bf16 v[52:55], v[148:151], v[164:167], v[52:55]
	v_mfma_f32_16x16x32_bf16 v[48:51], v[156:159], v[164:167], v[48:51]
	v_mfma_f32_16x16x32_bf16 v[48:51], v[152:155], v[160:163], v[48:51]
	v_mfma_f32_16x16x32_bf16 v[32:35], v[152:155], v[168:171], v[32:35]
	v_mfma_f32_16x16x32_bf16 v[32:35], v[156:159], v[172:175], v[32:35]
	v_mfma_f32_16x16x32_bf16 v[36:39], v[148:151], v[172:175], v[36:39]
	v_mfma_f32_16x16x32_bf16 v[36:39], v[136:139], v[168:171], v[36:39]
	v_mfma_f32_16x16x32_bf16 v[20:23], v[136:139], v[176:179], v[20:23]
	v_mfma_f32_16x16x32_bf16 v[20:23], v[148:151], v[180:183], v[20:23]
	v_mfma_f32_16x16x32_bf16 v[16:19], v[156:159], v[180:183], v[16:19]
	v_mfma_f32_16x16x32_bf16 v[16:19], v[152:155], v[176:179], v[16:19]
	v_mfma_f32_16x16x32_bf16 v[0:3], v[152:155], v[202:205], v[0:3]
	v_mfma_f32_16x16x32_bf16 v[0:3], v[156:159], v[228:231], v[0:3]
	v_mfma_f32_16x16x32_bf16 v[4:7], v[148:151], v[228:231], v[4:7]
	v_mfma_f32_16x16x32_bf16 v[4:7], v[136:139], v[202:205], v[4:7]
	s_setprio 0
	s_barrier
	s_add_i32 s58, 0, 0x18000
	s_add_i32 s59, 0, 0x1c000
	v_add_u32_e32 v124, s58, v211
	v_add_u32_e32 v156, s59, v211
	ds_read_b128 v[88:91], v124
	ds_read_b128 v[100:103], v124 offset:1024
	ds_read_b128 v[112:115], v124 offset:2048
	ds_read_b128 v[124:127], v124 offset:3072
	ds_read_b128 v[136:139], v156
	ds_read_b128 v[148:151], v156 offset:1024
	ds_read_b128 v[152:155], v156 offset:2048
	ds_read_b128 v[156:159], v156 offset:3072
	s_add_u32 s46, s46, 0x40000
	s_addc_u32 s47, s47, 0
	s_mov_b32 m0, s34
	v_lshl_add_u64 v[224:225], s[46:47], 0, v[184:185]
	ds_read_b128 v[160:163], v238 offset:32768
	ds_read_b128 v[164:167], v238 offset:33792
	ds_read_b128 v[168:171], v238 offset:34816
	ds_read_b128 v[172:175], v238 offset:35840
	ds_read_b128 v[176:179], v238 offset:36864
	ds_read_b128 v[180:183], v238 offset:37888
	ds_read_b128 v[202:205], v238 offset:38912
	ds_read_b128 v[228:231], v238 offset:39936
	global_load_lds_dwordx4 v[224:225], off
	v_lshl_add_u64 v[224:225], s[46:47], 0, v[188:189]
	s_mov_b32 m0, s35
	s_nop 0
	global_load_lds_dwordx4 v[224:225], off
	s_waitcnt vmcnt(8)
	s_waitcnt lgkmcnt(0)
	s_barrier
	s_setprio 1
	s_waitcnt lgkmcnt(0)
	v_mfma_f32_16x16x32_bf16 v[144:147], v[88:91], v[160:163], v[144:147]
	v_mfma_f32_16x16x32_bf16 v[144:147], v[100:103], v[164:167], v[144:147]
	v_mfma_f32_16x16x32_bf16 v[140:143], v[124:127], v[164:167], v[140:143]
	v_mfma_f32_16x16x32_bf16 v[140:143], v[112:115], v[160:163], v[140:143]
	v_mfma_f32_16x16x32_bf16 v[116:119], v[112:115], v[168:171], v[116:119]
	v_mfma_f32_16x16x32_bf16 v[116:119], v[124:127], v[172:175], v[116:119]
	v_mfma_f32_16x16x32_bf16 v[120:123], v[100:103], v[172:175], v[120:123]
	v_mfma_f32_16x16x32_bf16 v[120:123], v[88:91], v[168:171], v[120:123]
	v_mfma_f32_16x16x32_bf16 v[96:99], v[88:91], v[176:179], v[96:99]
	v_mfma_f32_16x16x32_bf16 v[96:99], v[100:103], v[180:183], v[96:99]
	v_mfma_f32_16x16x32_bf16 v[92:95], v[124:127], v[180:183], v[92:95]
	v_mfma_f32_16x16x32_bf16 v[92:95], v[112:115], v[176:179], v[92:95]
	v_mfma_f32_16x16x32_bf16 v[72:75], v[112:115], v[202:205], v[72:75]
	v_mfma_f32_16x16x32_bf16 v[72:75], v[124:127], v[228:231], v[72:75]
	v_mfma_f32_16x16x32_bf16 v[76:79], v[100:103], v[228:231], v[76:79]
	v_mfma_f32_16x16x32_bf16 v[76:79], v[88:91], v[202:205], v[76:79]
	s_setprio 0
	s_setprio 1
	v_mfma_f32_16x16x32_bf16 v[132:135], v[136:139], v[160:163], v[132:135]
	v_mfma_f32_16x16x32_bf16 v[132:135], v[148:151], v[164:167], v[132:135]
	v_mfma_f32_16x16x32_bf16 v[128:131], v[156:159], v[164:167], v[128:131]
	v_mfma_f32_16x16x32_bf16 v[128:131], v[152:155], v[160:163], v[128:131]
	v_mfma_f32_16x16x32_bf16 v[104:107], v[152:155], v[168:171], v[104:107]
	v_mfma_f32_16x16x32_bf16 v[104:107], v[156:159], v[172:175], v[104:107]
	v_mfma_f32_16x16x32_bf16 v[108:111], v[148:151], v[172:175], v[108:111]
	v_mfma_f32_16x16x32_bf16 v[108:111], v[136:139], v[168:171], v[108:111]
	v_mfma_f32_16x16x32_bf16 v[84:87], v[136:139], v[176:179], v[84:87]
	v_mfma_f32_16x16x32_bf16 v[84:87], v[148:151], v[180:183], v[84:87]
	v_mfma_f32_16x16x32_bf16 v[80:83], v[156:159], v[180:183], v[80:83]
	v_mfma_f32_16x16x32_bf16 v[80:83], v[152:155], v[176:179], v[80:83]
	v_mfma_f32_16x16x32_bf16 v[64:67], v[152:155], v[202:205], v[64:67]
	v_mfma_f32_16x16x32_bf16 v[64:67], v[156:159], v[228:231], v[64:67]
	v_mfma_f32_16x16x32_bf16 v[68:71], v[148:151], v[228:231], v[68:71]
	v_mfma_f32_16x16x32_bf16 v[68:71], v[136:139], v[202:205], v[68:71]
	s_setprio 0
	s_barrier
	s_add_i32 s46, s58, s2
	v_lshl_add_u64 v[208:209], v[208:209], 0, s[24:25]
	s_mov_b32 m0, s46
	ds_read_b128 v[160:163], v238 offset:49152
	ds_read_b128 v[164:167], v238 offset:50176
	ds_read_b128 v[168:171], v238 offset:51200
	ds_read_b128 v[172:175], v238 offset:52224
	ds_read_b128 v[176:179], v238 offset:53248
	ds_read_b128 v[180:183], v238 offset:54272
	ds_read_b128 v[202:205], v238 offset:55296
	ds_read_b128 v[228:231], v238 offset:56320
	global_load_lds_dwordx4 v[208:209], off
	s_add_i32 m0, s46, 0x2000
	s_add_u32 s44, s44, 0x40080
	v_lshl_add_u64 v[208:209], v[212:213], 0, s[24:25]
	s_addc_u32 s45, s45, 0
	s_add_i32 s46, s59, s2
	global_load_lds_dwordx4 v[208:209], off
	v_lshl_add_u64 v[208:209], s[44:45], 0, v[186:187]
	s_mov_b32 m0, s46
	s_nop 0
	global_load_lds_dwordx4 v[208:209], off
	v_lshl_add_u64 v[208:209], s[44:45], 0, v[190:191]
	s_add_i32 m0, s46, 0x2000
	s_nop 0
	global_load_lds_dwordx4 v[208:209], off
	v_lshl_add_u64 v[208:209], v[216:217], 0, s[24:25]
	s_mov_b32 m0, s49
	s_nop 0
	global_load_lds_dwordx4 v[208:209], off
	v_lshl_add_u64 v[208:209], v[220:221], 0, s[24:25]
	s_mov_b32 m0, s50
	s_nop 0
	global_load_lds_dwordx4 v[208:209], off
	s_waitcnt vmcnt(8)
	s_waitcnt lgkmcnt(0)
	s_barrier
	s_setprio 1
	s_waitcnt lgkmcnt(0)
	v_mfma_f32_16x16x32_bf16 v[60:63], v[88:91], v[160:163], v[60:63]
	v_mfma_f32_16x16x32_bf16 v[60:63], v[100:103], v[164:167], v[60:63]
	v_mfma_f32_16x16x32_bf16 v[56:59], v[124:127], v[164:167], v[56:59]
	v_mfma_f32_16x16x32_bf16 v[56:59], v[112:115], v[160:163], v[56:59]
	v_mfma_f32_16x16x32_bf16 v[40:43], v[112:115], v[168:171], v[40:43]
	v_mfma_f32_16x16x32_bf16 v[40:43], v[124:127], v[172:175], v[40:43]
	v_mfma_f32_16x16x32_bf16 v[44:47], v[100:103], v[172:175], v[44:47]
	v_mfma_f32_16x16x32_bf16 v[44:47], v[88:91], v[168:171], v[44:47]
	v_mfma_f32_16x16x32_bf16 v[28:31], v[88:91], v[176:179], v[28:31]
	v_mfma_f32_16x16x32_bf16 v[28:31], v[100:103], v[180:183], v[28:31]
	v_mfma_f32_16x16x32_bf16 v[24:27], v[124:127], v[180:183], v[24:27]
	v_mfma_f32_16x16x32_bf16 v[24:27], v[112:115], v[176:179], v[24:27]
	v_mfma_f32_16x16x32_bf16 v[8:11], v[112:115], v[202:205], v[8:11]
	v_mfma_f32_16x16x32_bf16 v[8:11], v[124:127], v[228:231], v[8:11]
	v_mfma_f32_16x16x32_bf16 v[12:15], v[100:103], v[228:231], v[12:15]
	v_mfma_f32_16x16x32_bf16 v[12:15], v[88:91], v[202:205], v[12:15]
	s_setprio 0
	s_setprio 1
	v_mfma_f32_16x16x32_bf16 v[52:55], v[136:139], v[160:163], v[52:55]
	v_mfma_f32_16x16x32_bf16 v[52:55], v[148:151], v[164:167], v[52:55]
	v_mfma_f32_16x16x32_bf16 v[48:51], v[156:159], v[164:167], v[48:51]
	v_mfma_f32_16x16x32_bf16 v[48:51], v[152:155], v[160:163], v[48:51]
	v_mfma_f32_16x16x32_bf16 v[32:35], v[152:155], v[168:171], v[32:35]
	v_mfma_f32_16x16x32_bf16 v[32:35], v[156:159], v[172:175], v[32:35]
	v_mfma_f32_16x16x32_bf16 v[36:39], v[148:151], v[172:175], v[36:39]
	v_mfma_f32_16x16x32_bf16 v[36:39], v[136:139], v[168:171], v[36:39]
	v_mfma_f32_16x16x32_bf16 v[20:23], v[136:139], v[176:179], v[20:23]
	v_mfma_f32_16x16x32_bf16 v[20:23], v[148:151], v[180:183], v[20:23]
	v_mfma_f32_16x16x32_bf16 v[16:19], v[156:159], v[180:183], v[16:19]
	v_mfma_f32_16x16x32_bf16 v[16:19], v[152:155], v[176:179], v[16:19]
	v_mfma_f32_16x16x32_bf16 v[0:3], v[152:155], v[202:205], v[0:3]
	v_mfma_f32_16x16x32_bf16 v[0:3], v[156:159], v[228:231], v[0:3]
	v_mfma_f32_16x16x32_bf16 v[4:7], v[148:151], v[228:231], v[4:7]
	v_mfma_f32_16x16x32_bf16 v[4:7], v[136:139], v[202:205], v[4:7]
	s_setprio 0
	s_barrier
	s_add_i32 s57, s57, 2
	s_add_u32 s42, s42, 0x100
	s_addc_u32 s43, s43, 0
	s_add_u32 s55, s55, 0x100
	s_addc_u32 s56, s56, 0
	s_cmp_gt_u32 s57, 13
	s_cbranch_scc0 .LBB0_646
	s_and_b64 vcc, exec, s[26:27]
	s_cbranch_vccz .LBB0_649
	s_barrier

.LBB0_751:
	ds_read_b128 v[156:159], v152
	ds_read_b128 v[160:163], v152 offset:1024
	ds_read_b128 v[164:167], v152 offset:2048
	ds_read_b128 v[168:171], v152 offset:3072
	ds_read_b128 v[172:175], v153
	ds_read_b128 v[176:179], v153 offset:1024
	ds_read_b128 v[180:183], v153 offset:2048
	ds_read_b128 v[184:187], v153 offset:3072
	s_add_u32 s38, s36, 0xfffc0080
	s_addc_u32 s39, s37, -1
	s_cmp_eq_u32 s54, 12
	s_cselect_b32 s41, s25, s39
	s_cselect_b32 s40, s50, s38
	s_cselect_b32 s39, s23, s53
	s_cselect_b32 s38, s51, s52
	v_lshl_add_u64 v[146:147], s[36:37], 0, v[138:139]
	s_add_i32 m0, s31, 0xc000
	ds_read_b128 v[188:191], v154
	ds_read_b128 v[192:195], v154 offset:1024
	ds_read_b128 v[196:199], v154 offset:2048
	ds_read_b128 v[200:203], v154 offset:3072
	ds_read_b128 v[204:207], v154 offset:4096
	ds_read_b128 v[208:211], v154 offset:5120
	ds_read_b128 v[216:219], v154 offset:6144
	ds_read_b128 v[220:223], v154 offset:7168
	global_load_lds_dwordx4 v[146:147], off
	v_lshl_add_u64 v[146:147], s[36:37], 0, v[140:141]
	s_add_i32 m0, s31, 0xe000
	s_nop 0
	global_load_lds_dwordx4 v[146:147], off
	s_waitcnt vmcnt(8)
	s_waitcnt lgkmcnt(0)
	s_barrier
	s_setprio 1
	s_waitcnt lgkmcnt(0)
	v_mfma_f32_16x16x32_bf16 v[124:127], v[156:159], v[188:191], v[124:127]
	v_mfma_f32_16x16x32_bf16 v[124:127], v[160:163], v[192:195], v[124:127]
	v_mfma_f32_16x16x32_bf16 v[120:123], v[168:171], v[192:195], v[120:123]
	v_mfma_f32_16x16x32_bf16 v[120:123], v[164:167], v[188:191], v[120:123]
	v_mfma_f32_16x16x32_bf16 v[104:107], v[164:167], v[196:199], v[104:107]
	v_mfma_f32_16x16x32_bf16 v[104:107], v[168:171], v[200:203], v[104:107]
	v_mfma_f32_16x16x32_bf16 v[108:111], v[160:163], v[200:203], v[108:111]
	v_mfma_f32_16x16x32_bf16 v[108:111], v[156:159], v[196:199], v[108:111]
	v_mfma_f32_16x16x32_bf16 v[92:95], v[156:159], v[204:207], v[92:95]
	v_mfma_f32_16x16x32_bf16 v[92:95], v[160:163], v[208:211], v[92:95]
	v_mfma_f32_16x16x32_bf16 v[88:91], v[168:171], v[208:211], v[88:91]
	v_mfma_f32_16x16x32_bf16 v[88:91], v[164:167], v[204:207], v[88:91]
	v_mfma_f32_16x16x32_bf16 v[72:75], v[164:167], v[216:219], v[72:75]
	v_mfma_f32_16x16x32_bf16 v[72:75], v[168:171], v[220:223], v[72:75]
	v_mfma_f32_16x16x32_bf16 v[76:79], v[160:163], v[220:223], v[76:79]
	v_mfma_f32_16x16x32_bf16 v[76:79], v[156:159], v[216:219], v[76:79]
	s_setprio 0
	s_setprio 1
	v_mfma_f32_16x16x32_bf16 v[116:119], v[172:175], v[188:191], v[116:119]
	v_mfma_f32_16x16x32_bf16 v[116:119], v[176:179], v[192:195], v[116:119]
	v_mfma_f32_16x16x32_bf16 v[112:115], v[184:187], v[192:195], v[112:115]
	v_mfma_f32_16x16x32_bf16 v[112:115], v[180:183], v[188:191], v[112:115]
	v_mfma_f32_16x16x32_bf16 v[96:99], v[180:183], v[196:199], v[96:99]
	v_mfma_f32_16x16x32_bf16 v[96:99], v[184:187], v[200:203], v[96:99]
	v_mfma_f32_16x16x32_bf16 v[100:103], v[176:179], v[200:203], v[100:103]
	v_mfma_f32_16x16x32_bf16 v[100:103], v[172:175], v[196:199], v[100:103]
	v_mfma_f32_16x16x32_bf16 v[84:87], v[172:175], v[204:207], v[84:87]
	v_mfma_f32_16x16x32_bf16 v[84:87], v[176:179], v[208:211], v[84:87]
	v_mfma_f32_16x16x32_bf16 v[80:83], v[184:187], v[208:211], v[80:83]
	v_mfma_f32_16x16x32_bf16 v[80:83], v[180:183], v[204:207], v[80:83]
	v_mfma_f32_16x16x32_bf16 v[64:67], v[180:183], v[216:219], v[64:67]
	v_mfma_f32_16x16x32_bf16 v[64:67], v[184:187], v[220:223], v[64:67]
	v_mfma_f32_16x16x32_bf16 v[68:71], v[176:179], v[220:223], v[68:71]
	v_mfma_f32_16x16x32_bf16 v[68:71], v[172:175], v[216:219], v[68:71]
	s_setprio 0
	s_barrier
	s_add_i32 s55, s47, s33
	v_lshl_add_u64 v[146:147], s[38:39], 0, v[132:133]
	s_mov_b32 m0, s55
	ds_read_b128 v[188:191], v154 offset:16384
	ds_read_b128 v[192:195], v154 offset:17408
	ds_read_b128 v[196:199], v154 offset:18432
	ds_read_b128 v[200:203], v154 offset:19456
	ds_read_b128 v[204:207], v154 offset:20480
	ds_read_b128 v[208:211], v154 offset:21504
	ds_read_b128 v[216:219], v154 offset:22528
	ds_read_b128 v[220:223], v154 offset:23552
	global_load_lds_dwordx4 v[146:147], off
	s_add_i32 m0, s55, 0x2000
	s_add_u32 s56, s38, 0x40000
	v_lshl_add_u64 v[212:213], s[38:39], 0, v[128:129]
	s_addc_u32 s57, s39, 0
	s_add_i32 s55, s48, s33
	global_load_lds_dwordx4 v[212:213], off
	v_lshl_add_u64 v[224:225], s[56:57], 0, v[132:133]
	s_mov_b32 m0, s55
	v_lshl_add_u64 v[226:227], s[40:41], 0, v[130:131]
	global_load_lds_dwordx4 v[224:225], off
	v_lshl_add_u64 v[224:225], s[56:57], 0, v[128:129]
	s_add_i32 m0, s55, 0x2000
	s_nop 0
	global_load_lds_dwordx4 v[224:225], off
	v_lshl_add_u64 v[224:225], s[40:41], 0, v[134:135]
	s_mov_b32 m0, s31
	s_nop 0
	global_load_lds_dwordx4 v[224:225], off
	s_mov_b32 m0, s34
	s_nop 0
	global_load_lds_dwordx4 v[226:227], off
	s_waitcnt vmcnt(8)
	s_waitcnt lgkmcnt(0)
	s_barrier
	s_setprio 1
	s_waitcnt lgkmcnt(0)
	v_mfma_f32_16x16x32_bf16 v[60:63], v[156:159], v[188:191], v[60:63]
	v_mfma_f32_16x16x32_bf16 v[60:63], v[160:163], v[192:195], v[60:63]
	v_mfma_f32_16x16x32_bf16 v[56:59], v[168:171], v[192:195], v[56:59]
	v_mfma_f32_16x16x32_bf16 v[56:59], v[164:167], v[188:191], v[56:59]
	v_mfma_f32_16x16x32_bf16 v[40:43], v[164:167], v[196:199], v[40:43]
	v_mfma_f32_16x16x32_bf16 v[40:43], v[168:171], v[200:203], v[40:43]
	v_mfma_f32_16x16x32_bf16 v[44:47], v[160:163], v[200:203], v[44:47]
	v_mfma_f32_16x16x32_bf16 v[44:47], v[156:159], v[196:199], v[44:47]
	v_mfma_f32_16x16x32_bf16 v[28:31], v[156:159], v[204:207], v[28:31]
	v_mfma_f32_16x16x32_bf16 v[28:31], v[160:163], v[208:211], v[28:31]
	v_mfma_f32_16x16x32_bf16 v[24:27], v[168:171], v[208:211], v[24:27]
	v_mfma_f32_16x16x32_bf16 v[24:27], v[164:167], v[204:207], v[24:27]
	v_mfma_f32_16x16x32_bf16 v[8:11], v[164:167], v[216:219], v[8:11]
	v_mfma_f32_16x16x32_bf16 v[8:11], v[168:171], v[220:223], v[8:11]
	v_mfma_f32_16x16x32_bf16 v[12:15], v[160:163], v[220:223], v[12:15]
	v_mfma_f32_16x16x32_bf16 v[12:15], v[156:159], v[216:219], v[12:15]
	s_setprio 0
	s_setprio 1
	v_mfma_f32_16x16x32_bf16 v[52:55], v[172:175], v[188:191], v[52:55]
	v_mfma_f32_16x16x32_bf16 v[52:55], v[176:179], v[192:195], v[52:55]
	v_mfma_f32_16x16x32_bf16 v[48:51], v[184:187], v[192:195], v[48:51]
	v_mfma_f32_16x16x32_bf16 v[48:51], v[180:183], v[188:191], v[48:51]
	v_mfma_f32_16x16x32_bf16 v[32:35], v[180:183], v[196:199], v[32:35]
	v_mfma_f32_16x16x32_bf16 v[32:35], v[184:187], v[200:203], v[32:35]
	v_mfma_f32_16x16x32_bf16 v[36:39], v[176:179], v[200:203], v[36:39]
	v_mfma_f32_16x16x32_bf16 v[36:39], v[172:175], v[196:199], v[36:39]
	v_mfma_f32_16x16x32_bf16 v[20:23], v[172:175], v[204:207], v[20:23]
	v_mfma_f32_16x16x32_bf16 v[20:23], v[176:179], v[208:211], v[20:23]
	v_mfma_f32_16x16x32_bf16 v[16:19], v[184:187], v[208:211], v[16:19]
	v_mfma_f32_16x16x32_bf16 v[16:19], v[180:183], v[204:207], v[16:19]
	v_mfma_f32_16x16x32_bf16 v[0:3], v[180:183], v[216:219], v[0:3]
	v_mfma_f32_16x16x32_bf16 v[0:3], v[184:187], v[220:223], v[0:3]
	v_mfma_f32_16x16x32_bf16 v[4:7], v[176:179], v[220:223], v[4:7]
	v_mfma_f32_16x16x32_bf16 v[4:7], v[172:175], v[216:219], v[4:7]
	s_setprio 0
	s_barrier
	s_add_i32 s55, 0, 0x18000
	v_add_u32_e32 v155, s55, v148
	s_add_i32 s56, 0, 0x1c000
	ds_read_b128 v[156:159], v155
	ds_read_b128 v[160:163], v155 offset:1024
	ds_read_b128 v[164:167], v155 offset:2048
	ds_read_b128 v[168:171], v155 offset:3072
	v_add_u32_e32 v155, s56, v148
	ds_read_b128 v[172:175], v155
	ds_read_b128 v[176:179], v155 offset:1024
	ds_read_b128 v[180:183], v155 offset:2048
	ds_read_b128 v[184:187], v155 offset:3072
	s_add_u32 s40, s40, 0x40000
	s_addc_u32 s41, s41, 0
	s_mov_b32 m0, s35
	v_lshl_add_u64 v[228:229], s[40:41], 0, v[134:135]
	ds_read_b128 v[188:191], v154 offset:32768
	ds_read_b128 v[192:195], v154 offset:33792
	ds_read_b128 v[196:199], v154 offset:34816
	ds_read_b128 v[200:203], v154 offset:35840
	ds_read_b128 v[204:207], v154 offset:36864
	ds_read_b128 v[208:211], v154 offset:37888
	ds_read_b128 v[216:219], v154 offset:38912
	ds_read_b128 v[220:223], v154 offset:39936
	global_load_lds_dwordx4 v[228:229], off
	v_lshl_add_u64 v[228:229], s[40:41], 0, v[130:131]
	s_mov_b32 m0, s42
	s_nop 0
	global_load_lds_dwordx4 v[228:229], off
	s_waitcnt vmcnt(8)
	s_waitcnt lgkmcnt(0)
	s_barrier
	s_setprio 1
	s_waitcnt lgkmcnt(0)
	v_mfma_f32_16x16x32_bf16 v[124:127], v[156:159], v[188:191], v[124:127]
	v_mfma_f32_16x16x32_bf16 v[124:127], v[160:163], v[192:195], v[124:127]
	v_mfma_f32_16x16x32_bf16 v[120:123], v[168:171], v[192:195], v[120:123]
	v_mfma_f32_16x16x32_bf16 v[120:123], v[164:167], v[188:191], v[120:123]
	v_mfma_f32_16x16x32_bf16 v[104:107], v[164:167], v[196:199], v[104:107]
	v_mfma_f32_16x16x32_bf16 v[104:107], v[168:171], v[200:203], v[104:107]
	v_mfma_f32_16x16x32_bf16 v[108:111], v[160:163], v[200:203], v[108:111]
	v_mfma_f32_16x16x32_bf16 v[108:111], v[156:159], v[196:199], v[108:111]
	v_mfma_f32_16x16x32_bf16 v[92:95], v[156:159], v[204:207], v[92:95]
	v_mfma_f32_16x16x32_bf16 v[92:95], v[160:163], v[208:211], v[92:95]
	v_mfma_f32_16x16x32_bf16 v[88:91], v[168:171], v[208:211], v[88:91]
	v_mfma_f32_16x16x32_bf16 v[88:91], v[164:167], v[204:207], v[88:91]
	v_mfma_f32_16x16x32_bf16 v[72:75], v[164:167], v[216:219], v[72:75]
	v_mfma_f32_16x16x32_bf16 v[72:75], v[168:171], v[220:223], v[72:75]
	v_mfma_f32_16x16x32_bf16 v[76:79], v[160:163], v[220:223], v[76:79]
	v_mfma_f32_16x16x32_bf16 v[76:79], v[156:159], v[216:219], v[76:79]
	s_setprio 0
	s_setprio 1
	v_mfma_f32_16x16x32_bf16 v[116:119], v[172:175], v[188:191], v[116:119]
	v_mfma_f32_16x16x32_bf16 v[116:119], v[176:179], v[192:195], v[116:119]
	v_mfma_f32_16x16x32_bf16 v[112:115], v[184:187], v[192:195], v[112:115]
	v_mfma_f32_16x16x32_bf16 v[112:115], v[180:183], v[188:191], v[112:115]
	v_mfma_f32_16x16x32_bf16 v[96:99], v[180:183], v[196:199], v[96:99]
	v_mfma_f32_16x16x32_bf16 v[96:99], v[184:187], v[200:203], v[96:99]
	v_mfma_f32_16x16x32_bf16 v[100:103], v[176:179], v[200:203], v[100:103]
	v_mfma_f32_16x16x32_bf16 v[100:103], v[172:175], v[196:199], v[100:103]
	v_mfma_f32_16x16x32_bf16 v[84:87], v[172:175], v[204:207], v[84:87]
	v_mfma_f32_16x16x32_bf16 v[84:87], v[176:179], v[208:211], v[84:87]
	v_mfma_f32_16x16x32_bf16 v[80:83], v[184:187], v[208:211], v[80:83]
	v_mfma_f32_16x16x32_bf16 v[80:83], v[180:183], v[204:207], v[80:83]
	v_mfma_f32_16x16x32_bf16 v[64:67], v[180:183], v[216:219], v[64:67]
	v_mfma_f32_16x16x32_bf16 v[64:67], v[184:187], v[220:223], v[64:67]
	v_mfma_f32_16x16x32_bf16 v[68:71], v[176:179], v[220:223], v[68:71]
	v_mfma_f32_16x16x32_bf16 v[68:71], v[172:175], v[216:219], v[68:71]
	s_setprio 0
	s_barrier
	s_add_i32 s40, s55, s33
	v_lshl_add_u64 v[146:147], v[146:147], 0, s[18:19]
	s_mov_b32 m0, s40
	ds_read_b128 v[188:191], v154 offset:49152
	ds_read_b128 v[192:195], v154 offset:50176
	ds_read_b128 v[196:199], v154 offset:51200
	ds_read_b128 v[200:203], v154 offset:52224
	ds_read_b128 v[204:207], v154 offset:53248
	ds_read_b128 v[208:211], v154 offset:54272
	ds_read_b128 v[216:219], v154 offset:55296
	ds_read_b128 v[220:223], v154 offset:56320
	global_load_lds_dwordx4 v[146:147], off
	s_add_i32 m0, s40, 0x2000
	s_add_u32 s38, s38, 0x40080
	v_lshl_add_u64 v[146:147], v[212:213], 0, s[18:19]
	s_addc_u32 s39, s39, 0
	s_add_i32 s40, s56, s33
	global_load_lds_dwordx4 v[146:147], off
	v_lshl_add_u64 v[146:147], s[38:39], 0, v[132:133]
	s_mov_b32 m0, s40
	s_nop 0
	global_load_lds_dwordx4 v[146:147], off
	v_lshl_add_u64 v[146:147], s[38:39], 0, v[128:129]
	s_add_i32 m0, s40, 0x2000
	s_nop 0
	global_load_lds_dwordx4 v[146:147], off
	v_lshl_add_u64 v[146:147], v[224:225], 0, s[18:19]
	s_mov_b32 m0, s44
	s_nop 0
	global_load_lds_dwordx4 v[146:147], off
	v_lshl_add_u64 v[146:147], v[226:227], 0, s[18:19]
	s_mov_b32 m0, s45
	s_nop 0
	global_load_lds_dwordx4 v[146:147], off
	s_waitcnt vmcnt(8)
	s_waitcnt lgkmcnt(0)
	s_barrier
	s_setprio 1
	s_waitcnt lgkmcnt(0)
	v_mfma_f32_16x16x32_bf16 v[60:63], v[156:159], v[188:191], v[60:63]
	v_mfma_f32_16x16x32_bf16 v[60:63], v[160:163], v[192:195], v[60:63]
	v_mfma_f32_16x16x32_bf16 v[56:59], v[168:171], v[192:195], v[56:59]
	v_mfma_f32_16x16x32_bf16 v[56:59], v[164:167], v[188:191], v[56:59]
	v_mfma_f32_16x16x32_bf16 v[40:43], v[164:167], v[196:199], v[40:43]
	v_mfma_f32_16x16x32_bf16 v[40:43], v[168:171], v[200:203], v[40:43]
	v_mfma_f32_16x16x32_bf16 v[44:47], v[160:163], v[200:203], v[44:47]
	v_mfma_f32_16x16x32_bf16 v[44:47], v[156:159], v[196:199], v[44:47]
	v_mfma_f32_16x16x32_bf16 v[28:31], v[156:159], v[204:207], v[28:31]
	v_mfma_f32_16x16x32_bf16 v[28:31], v[160:163], v[208:211], v[28:31]
	v_mfma_f32_16x16x32_bf16 v[24:27], v[168:171], v[208:211], v[24:27]
	v_mfma_f32_16x16x32_bf16 v[24:27], v[164:167], v[204:207], v[24:27]
	v_mfma_f32_16x16x32_bf16 v[8:11], v[164:167], v[216:219], v[8:11]
	v_mfma_f32_16x16x32_bf16 v[8:11], v[168:171], v[220:223], v[8:11]
	v_mfma_f32_16x16x32_bf16 v[12:15], v[160:163], v[220:223], v[12:15]
	v_mfma_f32_16x16x32_bf16 v[12:15], v[156:159], v[216:219], v[12:15]
	s_setprio 0
	s_setprio 1
	v_mfma_f32_16x16x32_bf16 v[52:55], v[172:175], v[188:191], v[52:55]
	v_mfma_f32_16x16x32_bf16 v[52:55], v[176:179], v[192:195], v[52:55]
	v_mfma_f32_16x16x32_bf16 v[48:51], v[184:187], v[192:195], v[48:51]
	v_mfma_f32_16x16x32_bf16 v[48:51], v[180:183], v[188:191], v[48:51]
	v_mfma_f32_16x16x32_bf16 v[32:35], v[180:183], v[196:199], v[32:35]
	v_mfma_f32_16x16x32_bf16 v[32:35], v[184:187], v[200:203], v[32:35]
	v_mfma_f32_16x16x32_bf16 v[36:39], v[176:179], v[200:203], v[36:39]
	v_mfma_f32_16x16x32_bf16 v[36:39], v[172:175], v[196:199], v[36:39]
	v_mfma_f32_16x16x32_bf16 v[20:23], v[172:175], v[204:207], v[20:23]
	v_mfma_f32_16x16x32_bf16 v[20:23], v[176:179], v[208:211], v[20:23]
	v_mfma_f32_16x16x32_bf16 v[16:19], v[184:187], v[208:211], v[16:19]
	v_mfma_f32_16x16x32_bf16 v[16:19], v[180:183], v[204:207], v[16:19]
	v_mfma_f32_16x16x32_bf16 v[0:3], v[180:183], v[216:219], v[0:3]
	v_mfma_f32_16x16x32_bf16 v[0:3], v[184:187], v[220:223], v[0:3]
	v_mfma_f32_16x16x32_bf16 v[4:7], v[176:179], v[220:223], v[4:7]
	v_mfma_f32_16x16x32_bf16 v[4:7], v[172:175], v[216:219], v[4:7]
	s_setprio 0
	s_barrier
	s_add_i32 s54, s54, 2
	s_add_u32 s36, s36, 0x100
	s_addc_u32 s37, s37, 0
	s_add_u32 s52, s52, 0x100
	s_addc_u32 s53, s53, 0
	s_cmp_gt_u32 s54, 13
	s_cbranch_scc0 .LBB0_751
	s_and_b64 vcc, exec, s[20:21]
	s_cbranch_vccz .LBB0_754
	s_barrier

.LBB0_828:
	ds_read_b128 v[142:145], v195
	ds_read_b128 v[146:149], v195 offset:1024
	ds_read_b128 v[150:153], v195 offset:2048
	ds_read_b128 v[154:157], v195 offset:3072
	ds_read_b128 v[158:161], v196
	ds_read_b128 v[162:165], v196 offset:1024
	ds_read_b128 v[166:169], v196 offset:2048
	ds_read_b128 v[170:173], v196 offset:3072
	s_add_u32 s40, s38, 0xfff00080
	s_addc_u32 s41, s39, -1
	s_cmp_eq_u32 s58, 60
	s_cselect_b32 s43, s27, s41
	s_cselect_b32 s42, s54, s40
	s_cselect_b32 s41, s25, s57
	s_cselect_b32 s40, s55, s56
	v_lshl_add_u64 v[190:191], s[38:39], 0, v[134:135]
	s_add_i32 m0, s2, 0xc000
	ds_read_b128 v[174:177], v197
	ds_read_b128 v[178:181], v197 offset:1024
	ds_read_b128 v[182:185], v197 offset:2048
	ds_read_b128 v[186:189], v197 offset:3072
	ds_read_b128 v[198:201], v197 offset:4096
	ds_read_b128 v[202:205], v197 offset:5120
	ds_read_b128 v[206:209], v197 offset:6144
	ds_read_b128 v[210:213], v197 offset:7168
	global_load_lds_dwordx4 v[190:191], off
	v_lshl_add_u64 v[190:191], s[38:39], 0, v[136:137]
	s_add_i32 m0, s2, 0xe000
	s_nop 0
	global_load_lds_dwordx4 v[190:191], off
	s_waitcnt vmcnt(8)
	s_waitcnt lgkmcnt(0)
	s_barrier
	s_setprio 1
	s_waitcnt lgkmcnt(0)
	v_mfma_f32_16x16x32_bf16 v[124:127], v[142:145], v[174:177], v[124:127]
	v_mfma_f32_16x16x32_bf16 v[124:127], v[146:149], v[178:181], v[124:127]
	v_mfma_f32_16x16x32_bf16 v[120:123], v[154:157], v[178:181], v[120:123]
	v_mfma_f32_16x16x32_bf16 v[120:123], v[150:153], v[174:177], v[120:123]
	v_mfma_f32_16x16x32_bf16 v[104:107], v[150:153], v[182:185], v[104:107]
	v_mfma_f32_16x16x32_bf16 v[104:107], v[154:157], v[186:189], v[104:107]
	v_mfma_f32_16x16x32_bf16 v[108:111], v[146:149], v[186:189], v[108:111]
	v_mfma_f32_16x16x32_bf16 v[108:111], v[142:145], v[182:185], v[108:111]
	v_mfma_f32_16x16x32_bf16 v[92:95], v[142:145], v[198:201], v[92:95]
	v_mfma_f32_16x16x32_bf16 v[92:95], v[146:149], v[202:205], v[92:95]
	v_mfma_f32_16x16x32_bf16 v[88:91], v[154:157], v[202:205], v[88:91]
	v_mfma_f32_16x16x32_bf16 v[88:91], v[150:153], v[198:201], v[88:91]
	v_mfma_f32_16x16x32_bf16 v[72:75], v[150:153], v[206:209], v[72:75]
	v_mfma_f32_16x16x32_bf16 v[72:75], v[154:157], v[210:213], v[72:75]
	v_mfma_f32_16x16x32_bf16 v[76:79], v[146:149], v[210:213], v[76:79]
	v_mfma_f32_16x16x32_bf16 v[76:79], v[142:145], v[206:209], v[76:79]
	s_setprio 0
	s_setprio 1
	v_mfma_f32_16x16x32_bf16 v[116:119], v[158:161], v[174:177], v[116:119]
	v_mfma_f32_16x16x32_bf16 v[116:119], v[162:165], v[178:181], v[116:119]
	v_mfma_f32_16x16x32_bf16 v[112:115], v[170:173], v[178:181], v[112:115]
	v_mfma_f32_16x16x32_bf16 v[112:115], v[166:169], v[174:177], v[112:115]
	v_mfma_f32_16x16x32_bf16 v[96:99], v[166:169], v[182:185], v[96:99]
	v_mfma_f32_16x16x32_bf16 v[96:99], v[170:173], v[186:189], v[96:99]
	v_mfma_f32_16x16x32_bf16 v[100:103], v[162:165], v[186:189], v[100:103]
	v_mfma_f32_16x16x32_bf16 v[100:103], v[158:161], v[182:185], v[100:103]
	v_mfma_f32_16x16x32_bf16 v[84:87], v[158:161], v[198:201], v[84:87]
	v_mfma_f32_16x16x32_bf16 v[84:87], v[162:165], v[202:205], v[84:87]
	v_mfma_f32_16x16x32_bf16 v[80:83], v[170:173], v[202:205], v[80:83]
	v_mfma_f32_16x16x32_bf16 v[80:83], v[166:169], v[198:201], v[80:83]
	v_mfma_f32_16x16x32_bf16 v[64:67], v[166:169], v[206:209], v[64:67]
	v_mfma_f32_16x16x32_bf16 v[64:67], v[170:173], v[210:213], v[64:67]
	v_mfma_f32_16x16x32_bf16 v[68:71], v[162:165], v[210:213], v[68:71]
	v_mfma_f32_16x16x32_bf16 v[68:71], v[158:161], v[206:209], v[68:71]
	s_setprio 0
	s_barrier
	s_add_i32 s59, s46, s3
	v_lshl_add_u64 v[190:191], s[40:41], 0, v[128:129]
	s_mov_b32 m0, s59
	ds_read_b128 v[174:177], v197 offset:16384
	ds_read_b128 v[178:181], v197 offset:17408
	ds_read_b128 v[182:185], v197 offset:18432
	ds_read_b128 v[186:189], v197 offset:19456
	ds_read_b128 v[198:201], v197 offset:20480
	ds_read_b128 v[202:205], v197 offset:21504
	ds_read_b128 v[206:209], v197 offset:22528
	ds_read_b128 v[210:213], v197 offset:23552
	global_load_lds_dwordx4 v[190:191], off
	s_add_i32 m0, s59, 0x2000
	s_add_u32 s62, s40, 0x100000
	v_lshl_add_u64 v[214:215], s[40:41], 0, v[130:131]
	s_addc_u32 s63, s41, 0
	s_add_i32 s59, s47, s3
	global_load_lds_dwordx4 v[214:215], off
	v_lshl_add_u64 v[216:217], s[62:63], 0, v[128:129]
	s_mov_b32 m0, s59
	v_lshl_add_u64 v[218:219], s[42:43], 0, v[130:131]
	global_load_lds_dwordx4 v[216:217], off
	v_lshl_add_u64 v[216:217], s[62:63], 0, v[130:131]
	s_add_i32 m0, s59, 0x2000
	s_nop 0
	global_load_lds_dwordx4 v[216:217], off
	v_lshl_add_u64 v[216:217], s[42:43], 0, v[128:129]
	s_mov_b32 m0, s2
	s_nop 0
	global_load_lds_dwordx4 v[216:217], off
	s_mov_b32 m0, s33
	s_nop 0
	global_load_lds_dwordx4 v[218:219], off
	s_waitcnt vmcnt(8)
	s_waitcnt lgkmcnt(0)
	s_barrier
	s_setprio 1
	s_waitcnt lgkmcnt(0)
	v_mfma_f32_16x16x32_bf16 v[60:63], v[142:145], v[174:177], v[60:63]
	v_mfma_f32_16x16x32_bf16 v[60:63], v[146:149], v[178:181], v[60:63]
	v_mfma_f32_16x16x32_bf16 v[56:59], v[154:157], v[178:181], v[56:59]
	v_mfma_f32_16x16x32_bf16 v[56:59], v[150:153], v[174:177], v[56:59]
	v_mfma_f32_16x16x32_bf16 v[40:43], v[150:153], v[182:185], v[40:43]
	v_mfma_f32_16x16x32_bf16 v[40:43], v[154:157], v[186:189], v[40:43]
	v_mfma_f32_16x16x32_bf16 v[44:47], v[146:149], v[186:189], v[44:47]
	v_mfma_f32_16x16x32_bf16 v[44:47], v[142:145], v[182:185], v[44:47]
	v_mfma_f32_16x16x32_bf16 v[28:31], v[142:145], v[198:201], v[28:31]
	v_mfma_f32_16x16x32_bf16 v[28:31], v[146:149], v[202:205], v[28:31]
	v_mfma_f32_16x16x32_bf16 v[24:27], v[154:157], v[202:205], v[24:27]
	v_mfma_f32_16x16x32_bf16 v[24:27], v[150:153], v[198:201], v[24:27]
	v_mfma_f32_16x16x32_bf16 v[8:11], v[150:153], v[206:209], v[8:11]
	v_mfma_f32_16x16x32_bf16 v[8:11], v[154:157], v[210:213], v[8:11]
	v_mfma_f32_16x16x32_bf16 v[12:15], v[146:149], v[210:213], v[12:15]
	v_mfma_f32_16x16x32_bf16 v[12:15], v[142:145], v[206:209], v[12:15]
	s_setprio 0
	s_setprio 1
	v_mfma_f32_16x16x32_bf16 v[52:55], v[158:161], v[174:177], v[52:55]
	v_mfma_f32_16x16x32_bf16 v[52:55], v[162:165], v[178:181], v[52:55]
	v_mfma_f32_16x16x32_bf16 v[48:51], v[170:173], v[178:181], v[48:51]
	v_mfma_f32_16x16x32_bf16 v[48:51], v[166:169], v[174:177], v[48:51]
	v_mfma_f32_16x16x32_bf16 v[32:35], v[166:169], v[182:185], v[32:35]
	v_mfma_f32_16x16x32_bf16 v[32:35], v[170:173], v[186:189], v[32:35]
	v_mfma_f32_16x16x32_bf16 v[36:39], v[162:165], v[186:189], v[36:39]
	v_mfma_f32_16x16x32_bf16 v[36:39], v[158:161], v[182:185], v[36:39]
	v_mfma_f32_16x16x32_bf16 v[20:23], v[158:161], v[198:201], v[20:23]
	v_mfma_f32_16x16x32_bf16 v[20:23], v[162:165], v[202:205], v[20:23]
	v_mfma_f32_16x16x32_bf16 v[16:19], v[170:173], v[202:205], v[16:19]
	v_mfma_f32_16x16x32_bf16 v[16:19], v[166:169], v[198:201], v[16:19]
	v_mfma_f32_16x16x32_bf16 v[0:3], v[166:169], v[206:209], v[0:3]
	v_mfma_f32_16x16x32_bf16 v[0:3], v[170:173], v[210:213], v[0:3]
	v_mfma_f32_16x16x32_bf16 v[4:7], v[162:165], v[210:213], v[4:7]
	v_mfma_f32_16x16x32_bf16 v[4:7], v[158:161], v[206:209], v[4:7]
	s_setprio 0
	s_barrier
	s_add_i32 s59, 0, 0x18000
	s_add_i32 s62, 0, 0x1c000
	v_add_u32_e32 v154, s59, v192
	v_add_u32_e32 v170, s62, v192
	ds_read_b128 v[142:145], v154
	ds_read_b128 v[146:149], v154 offset:1024
	ds_read_b128 v[150:153], v154 offset:2048
	ds_read_b128 v[154:157], v154 offset:3072
	ds_read_b128 v[158:161], v170
	ds_read_b128 v[162:165], v170 offset:1024
	ds_read_b128 v[166:169], v170 offset:2048
	ds_read_b128 v[170:173], v170 offset:3072
	s_add_u32 s42, s42, 0x100000
	s_addc_u32 s43, s43, 0
	s_mov_b32 m0, s34
	v_lshl_add_u64 v[220:221], s[42:43], 0, v[128:129]
	ds_read_b128 v[174:177], v197 offset:32768
	ds_read_b128 v[178:181], v197 offset:33792
	ds_read_b128 v[182:185], v197 offset:34816
	ds_read_b128 v[186:189], v197 offset:35840
	ds_read_b128 v[198:201], v197 offset:36864
	ds_read_b128 v[202:205], v197 offset:37888
	ds_read_b128 v[206:209], v197 offset:38912
	ds_read_b128 v[210:213], v197 offset:39936
	global_load_lds_dwordx4 v[220:221], off
	v_lshl_add_u64 v[220:221], s[42:43], 0, v[130:131]
	s_mov_b32 m0, s35
	s_nop 0
	global_load_lds_dwordx4 v[220:221], off
	s_waitcnt vmcnt(8)
	s_waitcnt lgkmcnt(0)
	s_barrier
	s_setprio 1
	s_waitcnt lgkmcnt(0)
	v_mfma_f32_16x16x32_bf16 v[124:127], v[142:145], v[174:177], v[124:127]
	v_mfma_f32_16x16x32_bf16 v[124:127], v[146:149], v[178:181], v[124:127]
	v_mfma_f32_16x16x32_bf16 v[120:123], v[154:157], v[178:181], v[120:123]
	v_mfma_f32_16x16x32_bf16 v[120:123], v[150:153], v[174:177], v[120:123]
	v_mfma_f32_16x16x32_bf16 v[104:107], v[150:153], v[182:185], v[104:107]
	v_mfma_f32_16x16x32_bf16 v[104:107], v[154:157], v[186:189], v[104:107]
	v_mfma_f32_16x16x32_bf16 v[108:111], v[146:149], v[186:189], v[108:111]
	v_mfma_f32_16x16x32_bf16 v[108:111], v[142:145], v[182:185], v[108:111]
	v_mfma_f32_16x16x32_bf16 v[92:95], v[142:145], v[198:201], v[92:95]
	v_mfma_f32_16x16x32_bf16 v[92:95], v[146:149], v[202:205], v[92:95]
	v_mfma_f32_16x16x32_bf16 v[88:91], v[154:157], v[202:205], v[88:91]
	v_mfma_f32_16x16x32_bf16 v[88:91], v[150:153], v[198:201], v[88:91]
	v_mfma_f32_16x16x32_bf16 v[72:75], v[150:153], v[206:209], v[72:75]
	v_mfma_f32_16x16x32_bf16 v[72:75], v[154:157], v[210:213], v[72:75]
	v_mfma_f32_16x16x32_bf16 v[76:79], v[146:149], v[210:213], v[76:79]
	v_mfma_f32_16x16x32_bf16 v[76:79], v[142:145], v[206:209], v[76:79]
	s_setprio 0
	s_setprio 1
	v_mfma_f32_16x16x32_bf16 v[116:119], v[158:161], v[174:177], v[116:119]
	v_mfma_f32_16x16x32_bf16 v[116:119], v[162:165], v[178:181], v[116:119]
	v_mfma_f32_16x16x32_bf16 v[112:115], v[170:173], v[178:181], v[112:115]
	v_mfma_f32_16x16x32_bf16 v[112:115], v[166:169], v[174:177], v[112:115]
	v_mfma_f32_16x16x32_bf16 v[96:99], v[166:169], v[182:185], v[96:99]
	v_mfma_f32_16x16x32_bf16 v[96:99], v[170:173], v[186:189], v[96:99]
	v_mfma_f32_16x16x32_bf16 v[100:103], v[162:165], v[186:189], v[100:103]
	v_mfma_f32_16x16x32_bf16 v[100:103], v[158:161], v[182:185], v[100:103]
	v_mfma_f32_16x16x32_bf16 v[84:87], v[158:161], v[198:201], v[84:87]
	v_mfma_f32_16x16x32_bf16 v[84:87], v[162:165], v[202:205], v[84:87]
	v_mfma_f32_16x16x32_bf16 v[80:83], v[170:173], v[202:205], v[80:83]
	v_mfma_f32_16x16x32_bf16 v[80:83], v[166:169], v[198:201], v[80:83]
	v_mfma_f32_16x16x32_bf16 v[64:67], v[166:169], v[206:209], v[64:67]
	v_mfma_f32_16x16x32_bf16 v[64:67], v[170:173], v[210:213], v[64:67]
	v_mfma_f32_16x16x32_bf16 v[68:71], v[162:165], v[210:213], v[68:71]
	v_mfma_f32_16x16x32_bf16 v[68:71], v[158:161], v[206:209], v[68:71]
	s_setprio 0
	s_barrier
	s_add_i32 s42, s59, s3
	v_lshl_add_u64 v[190:191], v[190:191], 0, s[8:9]
	s_mov_b32 m0, s42
	ds_read_b128 v[174:177], v197 offset:49152
	ds_read_b128 v[178:181], v197 offset:50176
	ds_read_b128 v[182:185], v197 offset:51200
	ds_read_b128 v[186:189], v197 offset:52224
	ds_read_b128 v[198:201], v197 offset:53248
	ds_read_b128 v[202:205], v197 offset:54272
	ds_read_b128 v[206:209], v197 offset:55296
	ds_read_b128 v[210:213], v197 offset:56320
	global_load_lds_dwordx4 v[190:191], off
	s_add_i32 m0, s42, 0x2000
	s_add_u32 s40, s40, 0x100080
	v_lshl_add_u64 v[190:191], v[214:215], 0, s[8:9]
	s_addc_u32 s41, s41, 0
	s_add_i32 s42, s62, s3
	global_load_lds_dwordx4 v[190:191], off
	v_lshl_add_u64 v[190:191], s[40:41], 0, v[128:129]
	s_mov_b32 m0, s42
	s_nop 0
	global_load_lds_dwordx4 v[190:191], off
	v_lshl_add_u64 v[190:191], s[40:41], 0, v[130:131]
	s_add_i32 m0, s42, 0x2000
	s_nop 0
	global_load_lds_dwordx4 v[190:191], off
	v_lshl_add_u64 v[190:191], v[216:217], 0, s[8:9]
	s_mov_b32 m0, s44
	s_nop 0
	global_load_lds_dwordx4 v[190:191], off
	v_lshl_add_u64 v[190:191], v[218:219], 0, s[8:9]
	s_mov_b32 m0, s45
	s_nop 0
	global_load_lds_dwordx4 v[190:191], off
	s_waitcnt vmcnt(8)
	s_waitcnt lgkmcnt(0)
	s_barrier
	s_setprio 1
	s_waitcnt lgkmcnt(0)
	v_mfma_f32_16x16x32_bf16 v[60:63], v[142:145], v[174:177], v[60:63]
	v_mfma_f32_16x16x32_bf16 v[60:63], v[146:149], v[178:181], v[60:63]
	v_mfma_f32_16x16x32_bf16 v[56:59], v[154:157], v[178:181], v[56:59]
	v_mfma_f32_16x16x32_bf16 v[56:59], v[150:153], v[174:177], v[56:59]
	v_mfma_f32_16x16x32_bf16 v[40:43], v[150:153], v[182:185], v[40:43]
	v_mfma_f32_16x16x32_bf16 v[40:43], v[154:157], v[186:189], v[40:43]
	v_mfma_f32_16x16x32_bf16 v[44:47], v[146:149], v[186:189], v[44:47]
	v_mfma_f32_16x16x32_bf16 v[44:47], v[142:145], v[182:185], v[44:47]
	v_mfma_f32_16x16x32_bf16 v[28:31], v[142:145], v[198:201], v[28:31]
	v_mfma_f32_16x16x32_bf16 v[28:31], v[146:149], v[202:205], v[28:31]
	v_mfma_f32_16x16x32_bf16 v[24:27], v[154:157], v[202:205], v[24:27]
	v_mfma_f32_16x16x32_bf16 v[24:27], v[150:153], v[198:201], v[24:27]
	v_mfma_f32_16x16x32_bf16 v[8:11], v[150:153], v[206:209], v[8:11]
	v_mfma_f32_16x16x32_bf16 v[8:11], v[154:157], v[210:213], v[8:11]
	v_mfma_f32_16x16x32_bf16 v[12:15], v[146:149], v[210:213], v[12:15]
	v_mfma_f32_16x16x32_bf16 v[12:15], v[142:145], v[206:209], v[12:15]
	s_setprio 0
	s_setprio 1
	v_mfma_f32_16x16x32_bf16 v[52:55], v[158:161], v[174:177], v[52:55]
	v_mfma_f32_16x16x32_bf16 v[52:55], v[162:165], v[178:181], v[52:55]
	v_mfma_f32_16x16x32_bf16 v[48:51], v[170:173], v[178:181], v[48:51]
	v_mfma_f32_16x16x32_bf16 v[48:51], v[166:169], v[174:177], v[48:51]
	v_mfma_f32_16x16x32_bf16 v[32:35], v[166:169], v[182:185], v[32:35]
	v_mfma_f32_16x16x32_bf16 v[32:35], v[170:173], v[186:189], v[32:35]
	v_mfma_f32_16x16x32_bf16 v[36:39], v[162:165], v[186:189], v[36:39]
	v_mfma_f32_16x16x32_bf16 v[36:39], v[158:161], v[182:185], v[36:39]
	v_mfma_f32_16x16x32_bf16 v[20:23], v[158:161], v[198:201], v[20:23]
	v_mfma_f32_16x16x32_bf16 v[20:23], v[162:165], v[202:205], v[20:23]
	v_mfma_f32_16x16x32_bf16 v[16:19], v[170:173], v[202:205], v[16:19]
	v_mfma_f32_16x16x32_bf16 v[16:19], v[166:169], v[198:201], v[16:19]
	v_mfma_f32_16x16x32_bf16 v[0:3], v[166:169], v[206:209], v[0:3]
	v_mfma_f32_16x16x32_bf16 v[0:3], v[170:173], v[210:213], v[0:3]
	v_mfma_f32_16x16x32_bf16 v[4:7], v[162:165], v[210:213], v[4:7]
	v_mfma_f32_16x16x32_bf16 v[4:7], v[158:161], v[206:209], v[4:7]
	s_setprio 0
	s_barrier
	s_add_i32 s58, s58, 2
	s_add_u32 s38, s38, 0x100
	s_addc_u32 s39, s39, 0
	s_add_u32 s56, s56, 0x100
	s_addc_u32 s57, s57, 0
	s_cmp_gt_u32 s58, 61
	s_cbranch_scc0 .LBB0_828
	s_and_b64 vcc, exec, s[10:11]
	s_cbranch_vccz .LBB0_831
	s_barrier
